# P1: write-through stores for the last TWO units of each workgroup (k and q rounds)
# speedup vs baseline: 1.0023x; 1.0023x over previous
.LBB0_168:
	s_lshl_b32 s12, s8, 8
	s_add_i32 s12, s12, s41
	v_or_b32_e32 v114, s12, v1
	s_mov_b64 s[0:1], -1
	s_cmp_gt_i32 s68, 11
	v_add_u32_e32 v174, 0x80, v114
	s_cbranch_scc0 .LBB0_171
	s_cmp_lt_u32 s68, 16
	s_cselect_b64 s[0:1], -1, 0
	s_lshl_b32 s13, s68, 8
	s_and_b64 s[8:9], s[0:1], exec
	s_cselect_b32 s8, s74, 0xfffff000
	s_cselect_b32 s20, 0x2000, s40
	s_add_i32 s13, s8, s13
	s_and_b64 s[8:9], s[0:1], exec
	s_cselect_b32 s8, s55, s49
	s_cselect_b32 s9, s54, s48
	v_mov_b32_e32 v117, s8
	s_sub_u32 s8, 32, s20
	v_mov_b32_e32 v116, s9
	s_subb_u32 s9, 0, 0
	v_mov_b32_e32 v115, s9
	v_cndmask_b32_e64 v119, v115, 0, s[4:5]
	v_mov_b32_e32 v115, s8
	s_and_b64 s[0:1], s[0:1], exec
	v_or_b32_e32 v154, s13, v176
	v_cndmask_b32_e64 v118, v115, 0, s[4:5]
	v_ashrrev_i32_e32 v115, 31, v114
	s_cselect_b32 s0, 10, 11
	v_lshl_add_u64 v[116:117], v[154:155], 1, v[116:117]
	v_lshlrev_b64 v[128:129], s0, v[114:115]
	v_cvt_pk_bf16_f32 v115, v142, v143
	v_cvt_pk_bf16_f32 v121, v144, v145
	v_cvt_pk_bf16_f32 v122, v138, v139
	v_cvt_pk_bf16_f32 v123, v140, v141
	v_cvt_pk_bf16_f32 v124, v134, v135
	v_mov_b32_e32 v154, v155
	v_cndmask_b32_e64 v120, v115, v124, s[4:5]
	v_cvt_pk_bf16_f32 v125, v136, v137
	v_cvt_pk_bf16_f32 v126, v130, v131
	v_cvt_pk_bf16_f32 v127, v132, v133
	v_lshl_add_u64 v[128:129], v[128:129], 1, v[116:117]
	v_lshlrev_b64 v[118:119], 1, v[118:119]
	v_mov_b32_dpp v154, v120 row_ror:8 row_mask:0xf bank_mask:0xf
	v_cndmask_b32_e64 v120, v154, v115, s[4:5]
	v_cndmask_b32_e64 v124, v124, v154, s[4:5]
	v_cndmask_b32_e64 v115, v121, v125, s[4:5]
	v_mov_b32_e32 v154, v155
	v_lshl_add_u64 v[182:183], v[128:129], 0, v[118:119]
	v_mov_b32_e32 v175, v155
	v_mov_b32_dpp v154, v115 row_ror:8 row_mask:0xf bank_mask:0xf
	v_cndmask_b32_e64 v121, v154, v121, s[4:5]
	v_cndmask_b32_e64 v125, v125, v154, s[4:5]
	v_cndmask_b32_e64 v115, v122, v126, s[4:5]
	v_mov_b32_e32 v154, v155
	s_nop 1
	v_mov_b32_dpp v154, v115 row_ror:8 row_mask:0xf bank_mask:0xf
	v_cndmask_b32_e64 v122, v154, v122, s[4:5]
	v_cndmask_b32_e64 v126, v126, v154, s[4:5]
	v_cndmask_b32_e64 v115, v123, v127, s[4:5]
	v_mov_b32_e32 v154, v155
	s_nop 1
	v_mov_b32_dpp v154, v115 row_ror:8 row_mask:0xf bank_mask:0xf
	v_mov_b32_e32 v115, s20
	v_cndmask_b32_e64 v115, 32, v115, s[4:5]
	v_cndmask_b32_e64 v123, v154, v123, s[4:5]
	v_cndmask_b32_e64 v127, v127, v154, s[4:5]
	v_lshlrev_b32_e32 v154, 1, v115
	s_cmp_lt_u32 s39, 5
	s_cbranch_scc0 .Lp1wt_0
	global_store_dwordx4 v[182:183], v[120:123], off
	s_branch .Lp1wt_0_e

.Lp1wt_0_e:
	s_nop 1
	v_lshl_add_u64 v[120:121], v[128:129], 0, v[154:155]
	s_cmp_lt_u32 s39, 5
	s_cbranch_scc0 .Lp1wt_1
	global_store_dwordx4 v[120:121], v[124:127], off
	s_branch .Lp1wt_1_e

.Lp1wt_1_e:
	v_or_b32_e32 v120, 16, v114
	v_ashrrev_i32_e32 v121, 31, v120
	v_lshlrev_b64 v[128:129], s0, v[120:121]
	v_cvt_pk_bf16_f32 v115, v110, v111
	v_cvt_pk_bf16_f32 v121, v112, v113
	v_cvt_pk_bf16_f32 v122, v106, v107
	v_cvt_pk_bf16_f32 v123, v108, v109
	v_cvt_pk_bf16_f32 v124, v102, v103
	v_cvt_pk_bf16_f32 v125, v104, v105
	v_cvt_pk_bf16_f32 v126, v98, v99
	v_cvt_pk_bf16_f32 v127, v100, v101
	v_lshl_add_u64 v[128:129], v[128:129], 1, v[116:117]
	v_cndmask_b32_e64 v120, v115, v124, s[4:5]
	v_lshl_add_u64 v[182:183], v[128:129], 0, v[118:119]
	s_nop 0
	v_mov_b32_dpp v175, v120 row_ror:8 row_mask:0xf bank_mask:0xf
	v_cndmask_b32_e64 v120, v175, v115, s[4:5]
	v_cndmask_b32_e64 v124, v124, v175, s[4:5]
	v_cndmask_b32_e64 v115, v121, v125, s[4:5]
	v_mov_b32_e32 v175, v155
	s_nop 1
	v_mov_b32_dpp v175, v115 row_ror:8 row_mask:0xf bank_mask:0xf
	v_cndmask_b32_e64 v121, v175, v121, s[4:5]
	v_cndmask_b32_e64 v125, v125, v175, s[4:5]
	v_cndmask_b32_e64 v115, v122, v126, s[4:5]
	v_mov_b32_e32 v175, v155
	s_nop 1
	v_mov_b32_dpp v175, v115 row_ror:8 row_mask:0xf bank_mask:0xf
	v_cndmask_b32_e64 v122, v175, v122, s[4:5]
	v_cndmask_b32_e64 v126, v126, v175, s[4:5]
	v_cndmask_b32_e64 v115, v123, v127, s[4:5]
	v_mov_b32_e32 v175, v155
	s_nop 1
	v_mov_b32_dpp v175, v115 row_ror:8 row_mask:0xf bank_mask:0xf
	v_cndmask_b32_e64 v123, v175, v123, s[4:5]
	v_cndmask_b32_e64 v127, v127, v175, s[4:5]
	s_cmp_lt_u32 s39, 5
	s_cbranch_scc0 .Lp1wt_2
	global_store_dwordx4 v[182:183], v[120:123], off
	s_branch .Lp1wt_2_e

.Lp1wt_2_e:
	v_mov_b32_e32 v175, v155
	s_nop 0
	v_lshl_add_u64 v[120:121], v[128:129], 0, v[154:155]
	s_cmp_lt_u32 s39, 5
	s_cbranch_scc0 .Lp1wt_3
	global_store_dwordx4 v[120:121], v[124:127], off
	s_branch .Lp1wt_3_e

.Lp1wt_3_e:
	v_or_b32_e32 v120, 32, v114
	v_ashrrev_i32_e32 v121, 31, v120
	v_lshlrev_b64 v[128:129], s0, v[120:121]
	v_cvt_pk_bf16_f32 v115, v94, v95
	v_cvt_pk_bf16_f32 v121, v96, v97
	v_cvt_pk_bf16_f32 v122, v90, v91
	v_cvt_pk_bf16_f32 v123, v92, v93
	v_cvt_pk_bf16_f32 v124, v86, v87
	v_cvt_pk_bf16_f32 v125, v88, v89
	v_cvt_pk_bf16_f32 v126, v82, v83
	v_cvt_pk_bf16_f32 v127, v84, v85
	v_lshl_add_u64 v[128:129], v[128:129], 1, v[116:117]
	v_cndmask_b32_e64 v120, v115, v124, s[4:5]
	v_lshl_add_u64 v[182:183], v[128:129], 0, v[118:119]
	s_nop 0
	v_mov_b32_dpp v175, v120 row_ror:8 row_mask:0xf bank_mask:0xf
	v_cndmask_b32_e64 v120, v175, v115, s[4:5]
	v_cndmask_b32_e64 v124, v124, v175, s[4:5]
	v_cndmask_b32_e64 v115, v121, v125, s[4:5]
	v_mov_b32_e32 v175, v155
	s_nop 1
	v_mov_b32_dpp v175, v115 row_ror:8 row_mask:0xf bank_mask:0xf
	v_cndmask_b32_e64 v121, v175, v121, s[4:5]
	v_cndmask_b32_e64 v125, v125, v175, s[4:5]
	v_cndmask_b32_e64 v115, v122, v126, s[4:5]
	v_mov_b32_e32 v175, v155
	s_nop 1
	v_mov_b32_dpp v175, v115 row_ror:8 row_mask:0xf bank_mask:0xf
	v_cndmask_b32_e64 v122, v175, v122, s[4:5]
	v_cndmask_b32_e64 v126, v126, v175, s[4:5]
	v_cndmask_b32_e64 v115, v123, v127, s[4:5]
	v_mov_b32_e32 v175, v155
	s_nop 1
	v_mov_b32_dpp v175, v115 row_ror:8 row_mask:0xf bank_mask:0xf
	v_cndmask_b32_e64 v123, v175, v123, s[4:5]
	v_cndmask_b32_e64 v127, v127, v175, s[4:5]
	s_cmp_lt_u32 s39, 5
	s_cbranch_scc0 .Lp1wt_4
	global_store_dwordx4 v[182:183], v[120:123], off
	s_branch .Lp1wt_4_e

.Lp1wt_5_e:
	v_or_b32_e32 v120, 48, v114
	v_ashrrev_i32_e32 v121, 31, v120
	v_lshlrev_b64 v[128:129], s0, v[120:121]
	v_cvt_pk_bf16_f32 v115, v78, v79
	v_cvt_pk_bf16_f32 v121, v80, v81
	v_cvt_pk_bf16_f32 v122, v74, v75
	v_cvt_pk_bf16_f32 v123, v76, v77
	v_cvt_pk_bf16_f32 v124, v70, v71
	v_cvt_pk_bf16_f32 v125, v72, v73
	v_cvt_pk_bf16_f32 v126, v66, v67
	v_cvt_pk_bf16_f32 v127, v68, v69
	v_lshl_add_u64 v[128:129], v[128:129], 1, v[116:117]
	v_cndmask_b32_e64 v120, v115, v124, s[4:5]
	v_lshl_add_u64 v[182:183], v[128:129], 0, v[118:119]
	s_nop 0
	v_mov_b32_dpp v175, v120 row_ror:8 row_mask:0xf bank_mask:0xf
	v_cndmask_b32_e64 v120, v175, v115, s[4:5]
	v_cndmask_b32_e64 v124, v124, v175, s[4:5]
	v_cndmask_b32_e64 v115, v121, v125, s[4:5]
	v_mov_b32_e32 v175, v155
	s_nop 1
	v_mov_b32_dpp v175, v115 row_ror:8 row_mask:0xf bank_mask:0xf
	v_cndmask_b32_e64 v121, v175, v121, s[4:5]
	v_cndmask_b32_e64 v125, v125, v175, s[4:5]
	v_cndmask_b32_e64 v115, v122, v126, s[4:5]
	v_mov_b32_e32 v175, v155
	s_nop 1
	v_mov_b32_dpp v175, v115 row_ror:8 row_mask:0xf bank_mask:0xf
	v_cndmask_b32_e64 v122, v175, v122, s[4:5]
	v_cndmask_b32_e64 v126, v126, v175, s[4:5]
	v_cndmask_b32_e64 v115, v123, v127, s[4:5]
	v_mov_b32_e32 v175, v155
	s_nop 1
	v_mov_b32_dpp v175, v115 row_ror:8 row_mask:0xf bank_mask:0xf
	v_cndmask_b32_e64 v123, v175, v123, s[4:5]
	v_cndmask_b32_e64 v127, v127, v175, s[4:5]
	s_cmp_lt_u32 s39, 5
	s_cbranch_scc0 .Lp1wt_6
	global_store_dwordx4 v[182:183], v[120:123], off
	s_branch .Lp1wt_6_e

.Lp1wt_6_e:
	v_ashrrev_i32_e32 v175, 31, v174
	s_nop 0
	v_lshl_add_u64 v[120:121], v[128:129], 0, v[154:155]
	s_cmp_lt_u32 s39, 5
	s_cbranch_scc0 .Lp1wt_7
	global_store_dwordx4 v[120:121], v[124:127], off
	s_branch .Lp1wt_7_e

.Lp1wt_7_e:
	v_lshlrev_b64 v[128:129], s0, v[174:175]
	v_cvt_pk_bf16_f32 v115, v62, v63
	v_cvt_pk_bf16_f32 v121, v64, v65
	v_cvt_pk_bf16_f32 v122, v58, v59
	v_cvt_pk_bf16_f32 v123, v60, v61
	s_nop 0
	v_cvt_pk_bf16_f32 v124, v54, v55
	v_mov_b32_e32 v175, v155
	v_cndmask_b32_e64 v120, v115, v124, s[4:5]
	v_cvt_pk_bf16_f32 v125, v56, v57
	v_cvt_pk_bf16_f32 v126, v50, v51
	v_cvt_pk_bf16_f32 v127, v52, v53
	v_lshl_add_u64 v[128:129], v[128:129], 1, v[116:117]
	v_lshl_add_u64 v[182:183], v[128:129], 0, v[118:119]
	v_mov_b32_dpp v175, v120 row_ror:8 row_mask:0xf bank_mask:0xf
	v_cndmask_b32_e64 v120, v175, v115, s[4:5]
	v_cndmask_b32_e64 v124, v124, v175, s[4:5]
	v_cndmask_b32_e64 v115, v121, v125, s[4:5]
	v_mov_b32_e32 v175, v155
	s_nop 1
	v_mov_b32_dpp v175, v115 row_ror:8 row_mask:0xf bank_mask:0xf
	v_cndmask_b32_e64 v121, v175, v121, s[4:5]
	v_cndmask_b32_e64 v125, v125, v175, s[4:5]
	v_cndmask_b32_e64 v115, v122, v126, s[4:5]
	v_mov_b32_e32 v175, v155
	s_nop 1
	v_mov_b32_dpp v175, v115 row_ror:8 row_mask:0xf bank_mask:0xf
	v_cndmask_b32_e64 v122, v175, v122, s[4:5]
	v_cndmask_b32_e64 v126, v126, v175, s[4:5]
	v_cndmask_b32_e64 v115, v123, v127, s[4:5]
	v_mov_b32_e32 v175, v155
	s_nop 1
	v_mov_b32_dpp v175, v115 row_ror:8 row_mask:0xf bank_mask:0xf
	v_cndmask_b32_e64 v123, v175, v123, s[4:5]
	v_cndmask_b32_e64 v127, v127, v175, s[4:5]
	s_cmp_lt_u32 s39, 5
	s_cbranch_scc0 .Lp1wt_8
	global_store_dwordx4 v[182:183], v[120:123], off
	s_branch .Lp1wt_8_e

.Lp1wt_9_e:
	v_add_u32_e32 v120, 0x90, v114
	v_ashrrev_i32_e32 v121, 31, v120
	v_lshlrev_b64 v[128:129], s0, v[120:121]
	v_cvt_pk_bf16_f32 v115, v46, v47
	v_cvt_pk_bf16_f32 v121, v48, v49
	v_cvt_pk_bf16_f32 v122, v42, v43
	v_cvt_pk_bf16_f32 v123, v44, v45
	v_cvt_pk_bf16_f32 v124, v38, v39
	v_cvt_pk_bf16_f32 v125, v40, v41
	v_cvt_pk_bf16_f32 v126, v34, v35
	v_cvt_pk_bf16_f32 v127, v36, v37
	v_lshl_add_u64 v[128:129], v[128:129], 1, v[116:117]
	v_cndmask_b32_e64 v120, v115, v124, s[4:5]
	v_lshl_add_u64 v[182:183], v[128:129], 0, v[118:119]
	s_nop 0
	v_mov_b32_dpp v175, v120 row_ror:8 row_mask:0xf bank_mask:0xf
	v_cndmask_b32_e64 v120, v175, v115, s[4:5]
	v_cndmask_b32_e64 v124, v124, v175, s[4:5]
	v_cndmask_b32_e64 v115, v121, v125, s[4:5]
	v_mov_b32_e32 v175, v155
	s_nop 1
	v_mov_b32_dpp v175, v115 row_ror:8 row_mask:0xf bank_mask:0xf
	v_cndmask_b32_e64 v121, v175, v121, s[4:5]
	v_cndmask_b32_e64 v125, v125, v175, s[4:5]
	v_cndmask_b32_e64 v115, v122, v126, s[4:5]
	v_mov_b32_e32 v175, v155
	s_nop 1
	v_mov_b32_dpp v175, v115 row_ror:8 row_mask:0xf bank_mask:0xf
	v_cndmask_b32_e64 v122, v175, v122, s[4:5]
	v_cndmask_b32_e64 v126, v126, v175, s[4:5]
	v_cndmask_b32_e64 v115, v123, v127, s[4:5]
	v_mov_b32_e32 v175, v155
	s_nop 1
	v_mov_b32_dpp v175, v115 row_ror:8 row_mask:0xf bank_mask:0xf
	v_cndmask_b32_e64 v123, v175, v123, s[4:5]
	v_cndmask_b32_e64 v127, v127, v175, s[4:5]
	s_cmp_lt_u32 s39, 5
	s_cbranch_scc0 .Lp1wt_10
	global_store_dwordx4 v[182:183], v[120:123], off
	s_branch .Lp1wt_10_e

.Lp1wt_11_e:
	v_add_u32_e32 v120, 0xa0, v114
	v_ashrrev_i32_e32 v121, 31, v120
	v_lshlrev_b64 v[128:129], s0, v[120:121]
	v_cvt_pk_bf16_f32 v115, v30, v31
	v_cvt_pk_bf16_f32 v121, v32, v33
	v_cvt_pk_bf16_f32 v122, v26, v27
	v_cvt_pk_bf16_f32 v123, v28, v29
	v_cvt_pk_bf16_f32 v124, v22, v23
	v_cvt_pk_bf16_f32 v125, v24, v25
	v_cvt_pk_bf16_f32 v126, v18, v19
	v_cvt_pk_bf16_f32 v127, v20, v21
	v_lshl_add_u64 v[128:129], v[128:129], 1, v[116:117]
	v_cndmask_b32_e64 v120, v115, v124, s[4:5]
	v_lshl_add_u64 v[182:183], v[128:129], 0, v[118:119]
	s_nop 0
	v_mov_b32_dpp v175, v120 row_ror:8 row_mask:0xf bank_mask:0xf
	v_cndmask_b32_e64 v120, v175, v115, s[4:5]
	v_cndmask_b32_e64 v124, v124, v175, s[4:5]
	v_cndmask_b32_e64 v115, v121, v125, s[4:5]
	v_mov_b32_e32 v175, v155
	s_nop 1
	v_mov_b32_dpp v175, v115 row_ror:8 row_mask:0xf bank_mask:0xf
	v_cndmask_b32_e64 v121, v175, v121, s[4:5]
	v_cndmask_b32_e64 v125, v125, v175, s[4:5]
	v_cndmask_b32_e64 v115, v122, v126, s[4:5]
	v_mov_b32_e32 v175, v155
	s_nop 1
	v_mov_b32_dpp v175, v115 row_ror:8 row_mask:0xf bank_mask:0xf
	v_cndmask_b32_e64 v122, v175, v122, s[4:5]
	v_cndmask_b32_e64 v126, v126, v175, s[4:5]
	v_cndmask_b32_e64 v115, v123, v127, s[4:5]
	v_mov_b32_e32 v175, v155
	s_nop 1
	v_mov_b32_dpp v175, v115 row_ror:8 row_mask:0xf bank_mask:0xf
	v_cndmask_b32_e64 v123, v175, v123, s[4:5]
	v_cndmask_b32_e64 v127, v127, v175, s[4:5]
	s_cmp_lt_u32 s39, 5
	s_cbranch_scc0 .Lp1wt_12
	global_store_dwordx4 v[182:183], v[120:123], off
	s_branch .Lp1wt_12_e

.Lp1wt_13_e:
	v_add_u32_e32 v120, 0xb0, v114
	v_ashrrev_i32_e32 v121, 31, v120
	v_lshlrev_b64 v[128:129], s0, v[120:121]
	v_cvt_pk_bf16_f32 v115, v14, v15
	v_cvt_pk_bf16_f32 v121, v16, v17
	v_cvt_pk_bf16_f32 v122, v10, v11
	v_cvt_pk_bf16_f32 v123, v12, v13
	v_cvt_pk_bf16_f32 v124, v6, v7
	v_cvt_pk_bf16_f32 v125, v8, v9
	v_cvt_pk_bf16_f32 v126, v2, v3
	v_cvt_pk_bf16_f32 v127, v4, v5
	v_lshl_add_u64 v[116:117], v[128:129], 1, v[116:117]
	v_cndmask_b32_e64 v120, v115, v124, s[4:5]
	v_lshl_add_u64 v[118:119], v[116:117], 0, v[118:119]
	v_lshl_add_u64 v[116:117], v[116:117], 0, v[154:155]
	v_mov_b32_dpp v175, v120 row_ror:8 row_mask:0xf bank_mask:0xf
	v_cndmask_b32_e64 v120, v175, v115, s[4:5]
	v_cndmask_b32_e64 v124, v124, v175, s[4:5]
	v_cndmask_b32_e64 v115, v121, v125, s[4:5]
	v_mov_b32_e32 v175, v155
	s_nop 1
	v_mov_b32_dpp v175, v115 row_ror:8 row_mask:0xf bank_mask:0xf
	v_cndmask_b32_e64 v121, v175, v121, s[4:5]
	v_cndmask_b32_e64 v125, v125, v175, s[4:5]
	v_cndmask_b32_e64 v115, v122, v126, s[4:5]
	v_mov_b32_e32 v175, v155
	s_nop 1
	v_mov_b32_dpp v175, v115 row_ror:8 row_mask:0xf bank_mask:0xf
	v_cndmask_b32_e64 v122, v175, v122, s[4:5]
	v_cndmask_b32_e64 v126, v126, v175, s[4:5]
	v_cndmask_b32_e64 v115, v123, v127, s[4:5]
	v_mov_b32_e32 v175, v155
	s_nop 1
	v_mov_b32_dpp v175, v115 row_ror:8 row_mask:0xf bank_mask:0xf
	v_cndmask_b32_e64 v123, v175, v123, s[4:5]
	v_cndmask_b32_e64 v127, v127, v175, s[4:5]
	s_cmp_lt_u32 s39, 5
	s_cbranch_scc0 .Lp1wt_14
	global_store_dwordx4 v[118:119], v[120:123], off
	s_branch .Lp1wt_14_e

.Lp1wt_14_e:
	s_cmp_lt_u32 s39, 5
	s_cbranch_scc0 .Lp1wt_15
	global_store_dwordx4 v[116:117], v[124:127], off
	s_branch .Lp1wt_15_e

.Lrope_pf2:
	s_lshl_b32 s1, s68, 1
	s_and_b32 s1, s1, 6
	s_or_b32 s1, s50, s1
	s_lshl_b32 s0, s0, 5
	s_or_b32 s0, s1, s0
	s_lshr_b32 s1, s12, 9
	s_and_b32 s1, s1, 0xffff8
	s_add_i32 s1, s1, s0
	s_lshl_b32 s1, s1, 12
	s_cmp_lt_u32 s68, 4
	s_cselect_b64 vcc, -1, 0
	v_cndmask_b32_e32 v175, 1.0, v181, vcc
	v_mul_f32_e32 v142, v175, v142
	v_mul_f32_e32 v143, v175, v143
	v_cvt_pk_bf16_f32 v142, v142, v143
	v_mul_f32_e32 v143, v175, v144
	v_mul_f32_e32 v144, v175, v145
	v_mul_f32_e32 v138, v175, v138
	v_mul_f32_e32 v139, v175, v139
	v_mul_f32_e32 v134, v175, v134
	v_mul_f32_e32 v135, v175, v135
	v_cvt_pk_bf16_f32 v143, v143, v144
	v_cvt_pk_bf16_f32 v144, v138, v139
	v_mul_f32_e32 v138, v175, v140
	v_mul_f32_e32 v139, v175, v141
	v_cvt_pk_bf16_f32 v140, v138, v139
	v_cvt_pk_bf16_f32 v134, v134, v135
	v_mul_f32_e32 v135, v175, v136
	v_mul_f32_e32 v136, v175, v137
	v_mul_f32_e32 v130, v175, v130
	v_mul_f32_e32 v131, v175, v131
	v_cvt_pk_bf16_f32 v135, v135, v136
	v_cvt_pk_bf16_f32 v136, v130, v131
	v_mul_f32_e32 v130, v175, v132
	v_mul_f32_e32 v131, v175, v133
	v_cvt_pk_bf16_f32 v137, v130, v131
	v_cndmask_b32_e64 v130, v142, v134, s[4:5]
	v_mov_b32_e32 v131, 0
	v_mov_b32_e32 v132, 0
	v_or_b32_e32 v184, s1, v182
	v_mov_b32_dpp v131, v130 row_ror:8 row_mask:0xf bank_mask:0xf
	v_cndmask_b32_e64 v130, v131, v142, s[4:5]
	v_cndmask_b32_e64 v134, v134, v131, s[4:5]
	v_cndmask_b32_e64 v131, v143, v135, s[4:5]
	v_mov_b32_e32 v133, 0
	v_ashrrev_i32_e32 v185, 31, v184
	v_mov_b32_dpp v132, v131 row_ror:8 row_mask:0xf bank_mask:0xf
	v_cndmask_b32_e64 v131, v132, v143, s[4:5]
	v_cndmask_b32_e64 v135, v135, v132, s[4:5]
	v_cndmask_b32_e64 v132, v144, v136, s[4:5]
	v_lshlrev_b64 v[184:185], 8, v[184:185]
	v_mov_b32_e32 v141, 0
	v_mov_b32_dpp v133, v132 row_ror:8 row_mask:0xf bank_mask:0xf
	v_cndmask_b32_e64 v132, v133, v144, s[4:5]
	v_cndmask_b32_e64 v136, v136, v133, s[4:5]
	v_cndmask_b32_e64 v133, v140, v137, s[4:5]
	v_lshl_add_u64 v[138:139], v[162:163], 0, v[184:185]
	v_lshlrev_b32_e32 v154, 1, v158
	v_mov_b32_dpp v141, v133 row_ror:8 row_mask:0xf bank_mask:0xf
	v_cndmask_b32_e64 v133, v141, v140, s[4:5]
	v_cndmask_b32_e64 v137, v137, v141, s[4:5]
	v_lshl_add_u64 v[140:141], v[156:157], 1, v[138:139]
	s_cmp_lt_u32 s39, 5
	s_cbranch_scc0 .Lp1wt_16
	global_store_dwordx4 v[140:141], v[130:133], off
	s_branch .Lp1wt_16_e

.Lp1wt_16_e:
	s_and_b64 vcc, exec, s[8:9]
	s_nop 0
	v_lshl_add_u64 v[130:131], v[138:139], 0, v[154:155]
	s_cmp_lt_u32 s39, 5
	s_cbranch_scc0 .Lp1wt_17
	global_store_dwordx4 v[130:131], v[134:137], off
	s_branch .Lp1wt_17_e

.Lrope_pf3:
	v_mul_f32_e32 v110, v175, v110
	v_mul_f32_e32 v111, v175, v111
	v_cvt_pk_bf16_f32 v110, v110, v111
	v_mul_f32_e32 v111, v175, v112
	v_mul_f32_e32 v112, v175, v113
	v_mul_f32_e32 v106, v175, v106
	v_mul_f32_e32 v107, v175, v107
	v_mul_f32_e32 v102, v175, v102
	v_mul_f32_e32 v103, v175, v103
	v_cvt_pk_bf16_f32 v111, v111, v112
	v_cvt_pk_bf16_f32 v112, v106, v107
	v_mul_f32_e32 v106, v175, v108
	v_mul_f32_e32 v107, v175, v109
	v_cvt_pk_bf16_f32 v108, v106, v107
	v_cvt_pk_bf16_f32 v102, v102, v103
	v_mul_f32_e32 v103, v175, v104
	v_mul_f32_e32 v104, v175, v105
	v_mul_f32_e32 v98, v175, v98
	v_mul_f32_e32 v99, v175, v99
	v_cvt_pk_bf16_f32 v103, v103, v104
	v_cvt_pk_bf16_f32 v104, v98, v99
	v_mul_f32_e32 v98, v175, v100
	v_mul_f32_e32 v99, v175, v101
	v_cvt_pk_bf16_f32 v105, v98, v99
	v_cndmask_b32_e64 v98, v110, v102, s[4:5]
	v_mov_b32_e32 v99, v155
	v_mov_b32_e32 v100, v155
	v_or_b32_e32 v130, s1, v130
	v_mov_b32_dpp v99, v98 row_ror:8 row_mask:0xf bank_mask:0xf
	v_cndmask_b32_e64 v98, v99, v110, s[4:5]
	v_cndmask_b32_e64 v102, v102, v99, s[4:5]
	v_cndmask_b32_e64 v99, v111, v103, s[4:5]
	v_mov_b32_e32 v101, v155
	v_ashrrev_i32_e32 v131, 31, v130
	v_mov_b32_dpp v100, v99 row_ror:8 row_mask:0xf bank_mask:0xf
	v_cndmask_b32_e64 v99, v100, v111, s[4:5]
	v_cndmask_b32_e64 v103, v103, v100, s[4:5]
	v_cndmask_b32_e64 v100, v112, v104, s[4:5]
	v_lshlrev_b64 v[130:131], 8, v[130:131]
	v_mov_b32_e32 v109, v155
	v_mov_b32_dpp v101, v100 row_ror:8 row_mask:0xf bank_mask:0xf
	v_cndmask_b32_e64 v100, v101, v112, s[4:5]
	v_cndmask_b32_e64 v104, v104, v101, s[4:5]
	v_cndmask_b32_e64 v101, v108, v105, s[4:5]
	v_lshl_add_u64 v[106:107], v[162:163], 0, v[130:131]
	s_and_b64 vcc, exec, s[8:9]
	v_mov_b32_dpp v109, v101 row_ror:8 row_mask:0xf bank_mask:0xf
	v_cndmask_b32_e64 v101, v109, v108, s[4:5]
	v_cndmask_b32_e64 v105, v105, v109, s[4:5]
	v_lshl_add_u64 v[108:109], v[156:157], 1, v[106:107]
	s_cmp_lt_u32 s39, 5
	s_cbranch_scc0 .Lp1wt_18
	global_store_dwordx4 v[108:109], v[98:101], off
	s_branch .Lp1wt_18_e

.Lp1wt_18_e:
	s_nop 1
	v_lshl_add_u64 v[98:99], v[106:107], 0, v[154:155]
	s_cmp_lt_u32 s39, 5
	s_cbranch_scc0 .Lp1wt_19
	global_store_dwordx4 v[98:99], v[102:105], off
	s_branch .Lp1wt_19_e

.Lrope_pf4:
	v_mul_f32_e32 v94, v175, v94
	v_mul_f32_e32 v95, v175, v95
	v_cvt_pk_bf16_f32 v94, v94, v95
	v_mul_f32_e32 v95, v175, v96
	v_mul_f32_e32 v96, v175, v97
	v_mul_f32_e32 v90, v175, v90
	v_mul_f32_e32 v91, v175, v91
	v_mul_f32_e32 v86, v175, v86
	v_mul_f32_e32 v87, v175, v87
	v_cvt_pk_bf16_f32 v95, v95, v96
	v_cvt_pk_bf16_f32 v96, v90, v91
	v_mul_f32_e32 v90, v175, v92
	v_mul_f32_e32 v91, v175, v93
	v_cvt_pk_bf16_f32 v92, v90, v91
	v_cvt_pk_bf16_f32 v86, v86, v87
	v_mul_f32_e32 v87, v175, v88
	v_mul_f32_e32 v88, v175, v89
	v_mul_f32_e32 v82, v175, v82
	v_mul_f32_e32 v83, v175, v83
	v_cvt_pk_bf16_f32 v87, v87, v88
	v_cvt_pk_bf16_f32 v88, v82, v83
	v_mul_f32_e32 v82, v175, v84
	v_mul_f32_e32 v83, v175, v85
	v_cvt_pk_bf16_f32 v89, v82, v83
	v_cndmask_b32_e64 v82, v94, v86, s[4:5]
	v_mov_b32_e32 v83, v155
	v_mov_b32_e32 v84, v155
	v_or_b32_e32 v98, s1, v98
	v_mov_b32_dpp v83, v82 row_ror:8 row_mask:0xf bank_mask:0xf
	v_cndmask_b32_e64 v82, v83, v94, s[4:5]
	v_cndmask_b32_e64 v86, v86, v83, s[4:5]
	v_cndmask_b32_e64 v83, v95, v87, s[4:5]
	v_mov_b32_e32 v85, v155
	v_ashrrev_i32_e32 v99, 31, v98
	v_mov_b32_dpp v84, v83 row_ror:8 row_mask:0xf bank_mask:0xf
	v_cndmask_b32_e64 v83, v84, v95, s[4:5]
	v_cndmask_b32_e64 v87, v87, v84, s[4:5]
	v_cndmask_b32_e64 v84, v96, v88, s[4:5]
	v_lshlrev_b64 v[98:99], 8, v[98:99]
	v_mov_b32_e32 v93, v155
	v_mov_b32_dpp v85, v84 row_ror:8 row_mask:0xf bank_mask:0xf
	v_cndmask_b32_e64 v84, v85, v96, s[4:5]
	v_cndmask_b32_e64 v88, v88, v85, s[4:5]
	v_cndmask_b32_e64 v85, v92, v89, s[4:5]
	v_lshl_add_u64 v[90:91], v[162:163], 0, v[98:99]
	s_and_b64 vcc, exec, s[8:9]
	v_mov_b32_dpp v93, v85 row_ror:8 row_mask:0xf bank_mask:0xf
	v_cndmask_b32_e64 v85, v93, v92, s[4:5]
	v_cndmask_b32_e64 v89, v89, v93, s[4:5]
	v_lshl_add_u64 v[92:93], v[156:157], 1, v[90:91]
	s_cmp_lt_u32 s39, 5
	s_cbranch_scc0 .Lp1wt_20
	global_store_dwordx4 v[92:93], v[82:85], off
	s_branch .Lp1wt_20_e

.Lp1wt_20_e:
	s_nop 1
	v_lshl_add_u64 v[82:83], v[90:91], 0, v[154:155]
	s_cmp_lt_u32 s39, 5
	s_cbranch_scc0 .Lp1wt_21
	global_store_dwordx4 v[82:83], v[86:89], off
	s_branch .Lp1wt_21_e

.Lrope_pf5:
	v_mul_f32_e32 v78, v175, v78
	v_mul_f32_e32 v79, v175, v79
	v_cvt_pk_bf16_f32 v78, v78, v79
	v_mul_f32_e32 v79, v175, v80
	v_mul_f32_e32 v80, v175, v81
	v_mul_f32_e32 v74, v175, v74
	v_mul_f32_e32 v75, v175, v75
	v_mul_f32_e32 v70, v175, v70
	v_mul_f32_e32 v71, v175, v71
	v_cvt_pk_bf16_f32 v79, v79, v80
	v_cvt_pk_bf16_f32 v80, v74, v75
	v_mul_f32_e32 v74, v175, v76
	v_mul_f32_e32 v75, v175, v77
	v_cvt_pk_bf16_f32 v76, v74, v75
	v_cvt_pk_bf16_f32 v70, v70, v71
	v_mul_f32_e32 v71, v175, v72
	v_mul_f32_e32 v72, v175, v73
	v_mul_f32_e32 v66, v175, v66
	v_mul_f32_e32 v67, v175, v67
	v_cvt_pk_bf16_f32 v71, v71, v72
	v_cvt_pk_bf16_f32 v72, v66, v67
	v_mul_f32_e32 v66, v175, v68
	v_mul_f32_e32 v67, v175, v69
	v_cvt_pk_bf16_f32 v73, v66, v67
	v_cndmask_b32_e64 v66, v78, v70, s[4:5]
	v_mov_b32_e32 v67, v155
	v_mov_b32_e32 v68, v155
	v_or_b32_e32 v82, s1, v82
	v_mov_b32_dpp v67, v66 row_ror:8 row_mask:0xf bank_mask:0xf
	v_cndmask_b32_e64 v66, v67, v78, s[4:5]
	v_cndmask_b32_e64 v70, v70, v67, s[4:5]
	v_cndmask_b32_e64 v67, v79, v71, s[4:5]
	v_mov_b32_e32 v69, v155
	v_ashrrev_i32_e32 v83, 31, v82
	v_mov_b32_dpp v68, v67 row_ror:8 row_mask:0xf bank_mask:0xf
	v_cndmask_b32_e64 v67, v68, v79, s[4:5]
	v_cndmask_b32_e64 v71, v71, v68, s[4:5]
	v_cndmask_b32_e64 v68, v80, v72, s[4:5]
	v_lshlrev_b64 v[82:83], 8, v[82:83]
	v_mov_b32_e32 v77, v155
	v_mov_b32_dpp v69, v68 row_ror:8 row_mask:0xf bank_mask:0xf
	v_cndmask_b32_e64 v68, v69, v80, s[4:5]
	v_cndmask_b32_e64 v72, v72, v69, s[4:5]
	v_cndmask_b32_e64 v69, v76, v73, s[4:5]
	v_lshl_add_u64 v[74:75], v[162:163], 0, v[82:83]
	s_and_b64 vcc, exec, s[8:9]
	v_mov_b32_dpp v77, v69 row_ror:8 row_mask:0xf bank_mask:0xf
	v_cndmask_b32_e64 v69, v77, v76, s[4:5]
	v_cndmask_b32_e64 v73, v73, v77, s[4:5]
	v_lshl_add_u64 v[76:77], v[156:157], 1, v[74:75]
	s_cmp_lt_u32 s39, 5
	s_cbranch_scc0 .Lp1wt_22
	global_store_dwordx4 v[76:77], v[66:69], off
	s_branch .Lp1wt_22_e

.Lp1wt_22_e:
	s_nop 1
	v_lshl_add_u64 v[66:67], v[74:75], 0, v[154:155]
	s_cmp_lt_u32 s39, 5
	s_cbranch_scc0 .Lp1wt_23
	global_store_dwordx4 v[66:67], v[70:73], off
	s_branch .Lp1wt_23_e

.Lrope_pf6:
	v_mul_f32_e32 v62, v175, v62
	v_mul_f32_e32 v63, v175, v63
	v_cvt_pk_bf16_f32 v62, v62, v63
	v_mul_f32_e32 v63, v175, v64
	v_mul_f32_e32 v64, v175, v65
	v_mul_f32_e32 v58, v175, v58
	v_mul_f32_e32 v59, v175, v59
	v_mul_f32_e32 v54, v175, v54
	v_mul_f32_e32 v55, v175, v55
	v_cvt_pk_bf16_f32 v63, v63, v64
	v_cvt_pk_bf16_f32 v64, v58, v59
	v_mul_f32_e32 v58, v175, v60
	v_mul_f32_e32 v59, v175, v61
	v_cvt_pk_bf16_f32 v60, v58, v59
	v_cvt_pk_bf16_f32 v54, v54, v55
	v_mul_f32_e32 v55, v175, v56
	v_mul_f32_e32 v56, v175, v57
	v_mul_f32_e32 v50, v175, v50
	v_mul_f32_e32 v51, v175, v51
	v_cvt_pk_bf16_f32 v55, v55, v56
	v_cvt_pk_bf16_f32 v56, v50, v51
	v_mul_f32_e32 v50, v175, v52
	v_mul_f32_e32 v51, v175, v53
	v_cvt_pk_bf16_f32 v57, v50, v51
	v_cndmask_b32_e64 v50, v62, v54, s[4:5]
	v_mov_b32_e32 v51, v155
	v_lshrrev_b32_e32 v67, 9, v174
	v_and_b32_e32 v67, 0xffff8, v67
	v_mov_b32_dpp v51, v50 row_ror:8 row_mask:0xf bank_mask:0xf
	v_cndmask_b32_e64 v50, v51, v62, s[4:5]
	v_cndmask_b32_e64 v54, v54, v51, s[4:5]
	v_cndmask_b32_e64 v51, v63, v55, s[4:5]
	v_mov_b32_e32 v52, v155
	v_add_lshl_u32 v67, v67, s0, 12
	v_or_b32_e32 v68, v67, v66
	v_mov_b32_dpp v52, v51 row_ror:8 row_mask:0xf bank_mask:0xf
	v_cndmask_b32_e64 v51, v52, v63, s[4:5]
	v_cndmask_b32_e64 v55, v55, v52, s[4:5]
	v_cndmask_b32_e64 v52, v64, v56, s[4:5]
	v_mov_b32_e32 v53, v155
	v_ashrrev_i32_e32 v69, 31, v68
	v_lshlrev_b64 v[68:69], 8, v[68:69]
	v_mov_b32_dpp v53, v52 row_ror:8 row_mask:0xf bank_mask:0xf
	v_cndmask_b32_e64 v52, v53, v64, s[4:5]
	v_cndmask_b32_e64 v56, v56, v53, s[4:5]
	v_cndmask_b32_e64 v53, v60, v57, s[4:5]
	v_mov_b32_e32 v61, v155
	v_lshl_add_u64 v[58:59], v[162:163], 0, v[68:69]
	s_and_b64 vcc, exec, s[8:9]
	v_mov_b32_dpp v61, v53 row_ror:8 row_mask:0xf bank_mask:0xf
	v_cndmask_b32_e64 v53, v61, v60, s[4:5]
	v_cndmask_b32_e64 v57, v57, v61, s[4:5]
	v_lshl_add_u64 v[60:61], v[156:157], 1, v[58:59]
	s_cmp_lt_u32 s39, 5
	s_cbranch_scc0 .Lp1wt_24
	global_store_dwordx4 v[60:61], v[50:53], off
	s_branch .Lp1wt_24_e

.Lp1wt_24_e:
	s_nop 1
	v_lshl_add_u64 v[50:51], v[58:59], 0, v[154:155]
	s_cmp_lt_u32 s39, 5
	s_cbranch_scc0 .Lp1wt_25
	global_store_dwordx4 v[50:51], v[54:57], off
	s_branch .Lp1wt_25_e

.Lrope_pf7:
	v_mul_f32_e32 v46, v175, v46
	v_mul_f32_e32 v47, v175, v47
	v_cvt_pk_bf16_f32 v46, v46, v47
	v_mul_f32_e32 v47, v175, v48
	v_mul_f32_e32 v48, v175, v49
	v_mul_f32_e32 v42, v175, v42
	v_mul_f32_e32 v43, v175, v43
	v_mul_f32_e32 v38, v175, v38
	v_mul_f32_e32 v39, v175, v39
	v_cvt_pk_bf16_f32 v47, v47, v48
	v_cvt_pk_bf16_f32 v48, v42, v43
	v_mul_f32_e32 v42, v175, v44
	v_mul_f32_e32 v43, v175, v45
	v_cvt_pk_bf16_f32 v44, v42, v43
	v_cvt_pk_bf16_f32 v38, v38, v39
	v_mul_f32_e32 v39, v175, v40
	v_mul_f32_e32 v40, v175, v41
	v_mul_f32_e32 v34, v175, v34
	v_mul_f32_e32 v35, v175, v35
	v_cvt_pk_bf16_f32 v39, v39, v40
	v_cvt_pk_bf16_f32 v40, v34, v35
	v_mul_f32_e32 v34, v175, v36
	v_mul_f32_e32 v35, v175, v37
	v_cvt_pk_bf16_f32 v41, v34, v35
	v_cndmask_b32_e64 v34, v46, v38, s[4:5]
	v_mov_b32_e32 v35, v155
	v_mov_b32_e32 v36, v155
	v_or_b32_e32 v50, v67, v50
	v_mov_b32_dpp v35, v34 row_ror:8 row_mask:0xf bank_mask:0xf
	v_cndmask_b32_e64 v34, v35, v46, s[4:5]
	v_cndmask_b32_e64 v38, v38, v35, s[4:5]
	v_cndmask_b32_e64 v35, v47, v39, s[4:5]
	v_mov_b32_e32 v37, v155
	v_ashrrev_i32_e32 v51, 31, v50
	v_mov_b32_dpp v36, v35 row_ror:8 row_mask:0xf bank_mask:0xf
	v_cndmask_b32_e64 v35, v36, v47, s[4:5]
	v_cndmask_b32_e64 v39, v39, v36, s[4:5]
	v_cndmask_b32_e64 v36, v48, v40, s[4:5]
	v_lshlrev_b64 v[50:51], 8, v[50:51]
	v_mov_b32_e32 v45, v155
	v_mov_b32_dpp v37, v36 row_ror:8 row_mask:0xf bank_mask:0xf
	v_cndmask_b32_e64 v36, v37, v48, s[4:5]
	v_cndmask_b32_e64 v40, v40, v37, s[4:5]
	v_cndmask_b32_e64 v37, v44, v41, s[4:5]
	v_lshl_add_u64 v[42:43], v[162:163], 0, v[50:51]
	s_and_b64 vcc, exec, s[8:9]
	v_mov_b32_dpp v45, v37 row_ror:8 row_mask:0xf bank_mask:0xf
	v_cndmask_b32_e64 v37, v45, v44, s[4:5]
	v_cndmask_b32_e64 v41, v41, v45, s[4:5]
	v_lshl_add_u64 v[44:45], v[156:157], 1, v[42:43]
	s_cmp_lt_u32 s39, 5
	s_cbranch_scc0 .Lp1wt_26
	global_store_dwordx4 v[44:45], v[34:37], off
	s_branch .Lp1wt_26_e

.Lp1wt_26_e:
	s_nop 1
	v_lshl_add_u64 v[34:35], v[42:43], 0, v[154:155]
	s_cmp_lt_u32 s39, 5
	s_cbranch_scc0 .Lp1wt_27
	global_store_dwordx4 v[34:35], v[38:41], off
	s_branch .Lp1wt_27_e

.Lrope_pf8:
	v_mul_f32_e32 v30, v175, v30
	v_mul_f32_e32 v31, v175, v31
	v_cvt_pk_bf16_f32 v30, v30, v31
	v_mul_f32_e32 v31, v175, v32
	v_mul_f32_e32 v32, v175, v33
	v_mul_f32_e32 v26, v175, v26
	v_mul_f32_e32 v27, v175, v27
	v_mul_f32_e32 v22, v175, v22
	v_mul_f32_e32 v23, v175, v23
	v_cvt_pk_bf16_f32 v31, v31, v32
	v_cvt_pk_bf16_f32 v32, v26, v27
	v_mul_f32_e32 v26, v175, v28
	v_mul_f32_e32 v27, v175, v29
	v_cvt_pk_bf16_f32 v28, v26, v27
	v_cvt_pk_bf16_f32 v22, v22, v23
	v_mul_f32_e32 v23, v175, v24
	v_mul_f32_e32 v24, v175, v25
	v_mul_f32_e32 v18, v175, v18
	v_mul_f32_e32 v19, v175, v19
	v_cvt_pk_bf16_f32 v23, v23, v24
	v_cvt_pk_bf16_f32 v24, v18, v19
	v_mul_f32_e32 v18, v175, v20
	v_mul_f32_e32 v19, v175, v21
	v_cvt_pk_bf16_f32 v25, v18, v19
	v_cndmask_b32_e64 v18, v30, v22, s[4:5]
	v_mov_b32_e32 v19, v155
	v_mov_b32_e32 v20, v155
	v_or_b32_e32 v34, v67, v34
	v_mov_b32_dpp v19, v18 row_ror:8 row_mask:0xf bank_mask:0xf
	v_cndmask_b32_e64 v18, v19, v30, s[4:5]
	v_cndmask_b32_e64 v22, v22, v19, s[4:5]
	v_cndmask_b32_e64 v19, v31, v23, s[4:5]
	v_mov_b32_e32 v21, v155
	v_ashrrev_i32_e32 v35, 31, v34
	v_mov_b32_dpp v20, v19 row_ror:8 row_mask:0xf bank_mask:0xf
	v_cndmask_b32_e64 v19, v20, v31, s[4:5]
	v_cndmask_b32_e64 v23, v23, v20, s[4:5]
	v_cndmask_b32_e64 v20, v32, v24, s[4:5]
	v_lshlrev_b64 v[34:35], 8, v[34:35]
	v_mov_b32_e32 v29, v155
	v_mov_b32_dpp v21, v20 row_ror:8 row_mask:0xf bank_mask:0xf
	v_cndmask_b32_e64 v20, v21, v32, s[4:5]
	v_cndmask_b32_e64 v24, v24, v21, s[4:5]
	v_cndmask_b32_e64 v21, v28, v25, s[4:5]
	v_lshl_add_u64 v[26:27], v[162:163], 0, v[34:35]
	s_and_b64 vcc, exec, s[8:9]
	v_mov_b32_dpp v29, v21 row_ror:8 row_mask:0xf bank_mask:0xf
	v_cndmask_b32_e64 v21, v29, v28, s[4:5]
	v_cndmask_b32_e64 v25, v25, v29, s[4:5]
	v_lshl_add_u64 v[28:29], v[156:157], 1, v[26:27]
	s_cmp_lt_u32 s39, 5
	s_cbranch_scc0 .Lp1wt_28
	global_store_dwordx4 v[28:29], v[18:21], off
	s_branch .Lp1wt_28_e

.Lp1wt_28_e:
	s_nop 1
	v_lshl_add_u64 v[18:19], v[26:27], 0, v[154:155]
	s_cmp_lt_u32 s39, 5
	s_cbranch_scc0 .Lp1wt_29
	global_store_dwordx4 v[18:19], v[22:25], off
	s_branch .Lp1wt_29_e

.LBB0_204:
	v_mul_f32_e32 v14, v175, v14
	v_mul_f32_e32 v15, v175, v15
	v_cvt_pk_bf16_f32 v14, v14, v15
	v_mul_f32_e32 v15, v175, v16
	v_mul_f32_e32 v16, v175, v17
	v_mul_f32_e32 v10, v175, v10
	v_mul_f32_e32 v11, v175, v11
	v_mul_f32_e32 v6, v175, v6
	v_mul_f32_e32 v7, v175, v7
	v_cvt_pk_bf16_f32 v15, v15, v16
	v_cvt_pk_bf16_f32 v16, v10, v11
	v_mul_f32_e32 v10, v175, v12
	v_mul_f32_e32 v11, v175, v13
	v_cvt_pk_bf16_f32 v12, v10, v11
	v_cvt_pk_bf16_f32 v6, v6, v7
	v_mul_f32_e32 v7, v175, v8
	v_mul_f32_e32 v8, v175, v9
	v_mul_f32_e32 v2, v175, v2
	v_mul_f32_e32 v3, v175, v3
	v_cvt_pk_bf16_f32 v7, v7, v8
	v_cvt_pk_bf16_f32 v8, v2, v3
	v_mul_f32_e32 v2, v175, v4
	v_mul_f32_e32 v3, v175, v5
	v_cvt_pk_bf16_f32 v9, v2, v3
	v_cndmask_b32_e64 v2, v14, v6, s[4:5]
	v_mov_b32_e32 v3, v155
	v_mov_b32_e32 v4, v155
	v_or_b32_e32 v18, v67, v18
	v_mov_b32_dpp v3, v2 row_ror:8 row_mask:0xf bank_mask:0xf
	v_cndmask_b32_e64 v2, v3, v14, s[4:5]
	v_cndmask_b32_e64 v6, v6, v3, s[4:5]
	v_cndmask_b32_e64 v3, v15, v7, s[4:5]
	v_mov_b32_e32 v5, v155
	v_ashrrev_i32_e32 v19, 31, v18
	v_mov_b32_dpp v4, v3 row_ror:8 row_mask:0xf bank_mask:0xf
	v_cndmask_b32_e64 v3, v4, v15, s[4:5]
	v_cndmask_b32_e64 v7, v7, v4, s[4:5]
	v_cndmask_b32_e64 v4, v16, v8, s[4:5]
	v_lshlrev_b64 v[18:19], 8, v[18:19]
	v_mov_b32_e32 v13, v155
	v_mov_b32_dpp v5, v4 row_ror:8 row_mask:0xf bank_mask:0xf
	v_cndmask_b32_e64 v4, v5, v16, s[4:5]
	v_cndmask_b32_e64 v8, v8, v5, s[4:5]
	v_cndmask_b32_e64 v5, v12, v9, s[4:5]
	v_lshl_add_u64 v[10:11], v[162:163], 0, v[18:19]
	s_nop 0
	v_mov_b32_dpp v13, v5 row_ror:8 row_mask:0xf bank_mask:0xf
	v_cndmask_b32_e64 v5, v13, v12, s[4:5]
	v_cndmask_b32_e64 v9, v9, v13, s[4:5]
	v_lshl_add_u64 v[12:13], v[156:157], 1, v[10:11]
	s_cmp_lt_u32 s39, 5
	s_cbranch_scc0 .Lp1wt_30
	global_store_dwordx4 v[12:13], v[2:5], off
	s_branch .Lp1wt_30_e

.Lp1wt_30_e:
	s_nop 1
	v_lshl_add_u64 v[2:3], v[10:11], 0, v[154:155]
	s_cmp_lt_u32 s39, 5
	s_cbranch_scc0 .Lp1wt_31
	global_store_dwordx4 v[2:3], v[6:9], off
	s_branch .Lp1wt_31_e
